# rwkv_pass_b for the latent half rewritten by hand: chain state rows split over 4 workgroups (128 WGs), transposed f32 MFMA with Pm straight from global, 2-step register prefetch
# speedup vs baseline: 1.0502x; 1.0502x over previous
.LBB0_710:
	s_or_b64 exec, exec, s[0:1]
	s_and_b64 s[0:1], s[66:67], exec
	s_cselect_b32 s4, 0x200, 32
	s_waitcnt vmcnt(6) lgkmcnt(0)
	v_mov_b32_e32 v2, v177
	s_cmp_ge_i32 s72, s4
	s_barrier
	s_cmp_lg_u32 s68, 0
	s_cbranch_scc1 .Lrb1_start
	s_cmp_ge_i32 s72, s4
	s_cbranch_scc1 .LBB0_737
	v_lshlrev_b32_e32 v0, 3, v2
	s_and_b64 s[0:1], s[66:67], exec
	s_waitcnt vmcnt(3)
	v_and_b32_e32 v6, 56, v0
	v_lshrrev_b32_e32 v0, 5, v2
	v_and_b32_e32 v3, 2, v0
	v_ashrrev_i32_e32 v5, 3, v2
	s_movk_i32 s0, 0x44
	v_and_b32_e32 v4, 15, v2
	v_bfe_u32 v29, v2, 4, 2
	v_and_b32_e32 v0, -16, v5
	v_lshlrev_b32_e32 v26, 6, v5
	v_mul_lo_u32 v8, v5, s0
	v_bfi_b32 v5, -16, v5, v2
	s_movk_i32 s0, 0x110
	v_lshlrev_b32_e32 v86, 6, v3
	v_lshlrev_b32_e32 v28, 4, v3
	v_or_b32_e32 v3, 1, v3
	v_readlane_b32 s40, v252, 2
	v_lshl_or_b32 v7, v29, 2, v0
	v_ashrrev_i32_e32 v27, 31, v26
	v_lshlrev_b32_e32 v0, 2, v4
	v_mul_lo_u32 v85, v5, s0
	v_add_u32_e32 v5, 0, v86
	v_lshlrev_b32_e32 v32, 4, v3
	v_lshlrev_b32_e32 v88, 6, v3
	v_mul_u32_u24_e32 v3, 0x110, v29
	v_readlane_b32 s46, v252, 8
	v_readlane_b32 s47, v252, 9
	v_add_u32_e32 v82, 0, v0
	v_add3_u32 v89, v5, v3, v0
	v_lshl_add_u64 v[48:49], s[46:47], 0, v[0:1]
	v_and_b32_e32 v0, 7, v2
	s_waitcnt vmcnt(0)
	v_lshlrev_b64 v[54:55], 2, v[26:27]
	v_lshlrev_b32_e32 v30, 6, v7
	v_or_b32_e32 v12, v28, v4
	v_lshl_or_b32 v54, v0, 5, v54
	v_and_b32_e32 v0, 0xfffffc00, v26
	v_lshlrev_b32_e32 v2, 8, v29
	v_lshlrev_b32_e32 v83, 2, v8
	v_or_b32_e32 v34, 0xc0, v30
	v_or_b32_e32 v8, 64, v30
	v_or_b32_e32 v10, 0x80, v30
	v_or3_b32 v2, v0, v2, v12
	v_or_b32_e32 v36, v30, v12
	v_or_b32_e32 v38, v8, v12
	v_or_b32_e32 v40, v10, v12
	v_or_b32_e32 v13, v32, v4
	v_or_b32_e32 v50, v34, v12
	v_or_b32_e32 v12, 64, v2
	v_or_b32_e32 v42, v30, v13
	v_or_b32_e32 v44, v8, v13
	v_or_b32_e32 v46, v10, v13
	v_or_b32_e32 v52, v34, v13
	v_ashrrev_i32_e32 v13, 31, v12
	v_lshl_add_u64 v[58:59], v[12:13], 2, v[124:125]
	v_or_b32_e32 v12, 0x80, v2
	v_ashrrev_i32_e32 v13, 31, v12
	v_lshl_add_u64 v[60:61], v[12:13], 2, v[124:125]
	v_or_b32_e32 v12, 0xc0, v2
	v_ashrrev_i32_e32 v13, 31, v12
	v_lshl_add_u64 v[62:63], v[12:13], 2, v[124:125]
	v_or_b32_e32 v12, 16, v2
	v_ashrrev_i32_e32 v13, 31, v12
	v_lshl_add_u64 v[64:65], v[12:13], 2, v[124:125]
	v_or_b32_e32 v12, 0x50, v2
	v_ashrrev_i32_e32 v3, 31, v2
	v_ashrrev_i32_e32 v13, 31, v12
	v_lshl_add_u64 v[56:57], v[2:3], 2, v[124:125]
	v_lshl_add_u64 v[66:67], v[12:13], 2, v[124:125]
	v_or_b32_e32 v12, 0x90, v2
	v_or_b32_e32 v2, 0xd0, v2
	v_lshlrev_b32_e32 v33, 2, v6
	v_mul_lo_u32 v87, v7, s0
	v_add_u32_e32 v7, v82, v86
	v_add_u32_e32 v14, v82, v88
	v_ashrrev_i32_e32 v9, 31, v8
	v_ashrrev_i32_e32 v11, 31, v10
	v_ashrrev_i32_e32 v13, 31, v12
	v_ashrrev_i32_e32 v3, 31, v2
	s_cselect_b32 s5, 4, 64
	v_add3_u32 v84, 0, v33, v83
	v_ashrrev_i32_e32 v31, 31, v30
	v_ashrrev_i32_e32 v35, 31, v34
	v_ashrrev_i32_e32 v37, 31, v36
	v_ashrrev_i32_e32 v39, 31, v38
	v_ashrrev_i32_e32 v41, 31, v40
	v_ashrrev_i32_e32 v43, 31, v42
	v_ashrrev_i32_e32 v45, 31, v44
	v_ashrrev_i32_e32 v47, 31, v46
	v_ashrrev_i32_e32 v51, 31, v50
	v_ashrrev_i32_e32 v53, 31, v52
	v_lshl_add_u64 v[68:69], v[12:13], 2, v[124:125]
	v_lshl_add_u64 v[70:71], v[2:3], 2, v[124:125]
	v_lshlrev_b32_e32 v72, 2, v6
	v_add_u32_e32 v90, v7, v87
	v_add_u32_e32 v91, v14, v87
	v_lshlrev_b32_e32 v74, 2, v4
	v_lshlrev_b64 v[76:77], 2, v[8:9]
	v_lshlrev_b64 v[78:79], 2, v[10:11]
	s_mov_b32 s10, s72
	v_readlane_b32 s41, v252, 3
	v_readlane_b32 s42, v252, 4
	v_readlane_b32 s43, v252, 5
	v_readlane_b32 s44, v252, 6
	v_readlane_b32 s45, v252, 7
	v_readlane_b32 s48, v252, 10
	v_readlane_b32 s49, v252, 11
	v_readlane_b32 s50, v252, 12
	v_readlane_b32 s51, v252, 13
	v_readlane_b32 s52, v252, 14
	v_readlane_b32 s53, v252, 15
	v_readlane_b32 s54, v252, 16
	v_readlane_b32 s55, v252, 17
	s_branch .LBB0_713

.Lrb1_start:
	s_waitcnt vmcnt(0) lgkmcnt(0)
	s_cmp_gt_u32 s72, 127
	s_cbranch_scc1 .Lrb1_done
	v_lshrrev_b32_e32 v0, 6, v177
	v_and_b32_e32 v2, 63, v177
	v_readfirstlane_b32 s0, v0
	s_nop 3
	s_cmp_gt_u32 s0, 3
	s_cbranch_scc1 .Lrb1_helper
	s_and_b32 s1, s72, 7
	s_lshr_b32 s5, s72, 5
	s_lshl_b32 s5, s5, 3
	s_or_b32 s1, s1, s5
	s_bfe_u32 s5, s72, 0x20003
	s_lshl_b32 s6, s1, 21
	s_add_u32 s38, s76, s6
	s_addc_u32 s39, s77, 0
	s_add_u32 s38, s38, 0xb980000
	s_addc_u32 s39, s39, 0
	s_mov_b32 s40, s38
	s_mov_b32 s41, s39
	s_lshr_b32 s6, s1, 4
	s_and_b32 s7, s1, 1
	s_lshl_b32 s6, s6, 1
	s_or_b32 s6, s6, s7
	s_bfe_u32 s7, s1, 0x30001
	s_lshl_b32 s6, s6, 3
	s_or_b32 s6, s6, s7
	s_lshl_b32 s6, s6, 14
	v_readlane_b32 s42, v252, 8
	v_readlane_b32 s43, v252, 9
	s_nop 3
	s_add_u32 s42, s42, s6
	s_addc_u32 s43, s43, 0
	v_and_b32_e32 v3, 15, v2
	v_lshrrev_b32_e32 v4, 4, v2
	s_lshl_b32 s6, s5, 12
	s_lshl_b32 s7, s0, 6
	s_add_u32 s6, s6, s7
	v_lshlrev_b32_e32 v5, 8, v3
	v_lshl_add_u32 v5, v4, 4, v5
	v_add_u32_e32 v5, s6, v5
	s_add_u32 s7, s7, 0x4000
	v_lshlrev_b32_e32 v6, 8, v4
	v_lshl_add_u32 v6, v3, 2, v6
	v_add_u32_e32 v6, s7, v6
	v_add_u32_e32 v7, 0x1000, v6
	v_add_u32_e32 v8, 0x2000, v6
	v_add_u32_e32 v9, 0x3000, v6
	v_mul_u32_u24_e32 v0, 0x110, v3
	v_lshl_add_u32 v10, v4, 2, v0
	v_lshl_add_u32 v11, v4, 4, v0
	v_add_u32_e32 v11, s7, v11
	v_subrev_u32_e32 v11, 0x4000, v11
	global_load_dwordx4 v[12:15], v5, s[42:43]
	global_load_dwordx4 v[56:59], v5, s[38:39]
	global_load_dword v40, v6, s[38:39]
	global_load_dword v41, v6, s[38:39] offset:1024
	global_load_dword v42, v6, s[38:39] offset:2048
	global_load_dword v43, v6, s[38:39] offset:3072
	global_load_dword v44, v7, s[38:39]
	global_load_dword v45, v7, s[38:39] offset:1024
	global_load_dword v46, v7, s[38:39] offset:2048
	global_load_dword v47, v7, s[38:39] offset:3072
	global_load_dword v48, v8, s[38:39]
	global_load_dword v49, v8, s[38:39] offset:1024
	global_load_dword v50, v8, s[38:39] offset:2048
	global_load_dword v51, v8, s[38:39] offset:3072
	global_load_dword v52, v9, s[38:39]
	global_load_dword v53, v9, s[38:39] offset:1024
	global_load_dword v54, v9, s[38:39] offset:2048
	global_load_dword v55, v9, s[38:39] offset:3072
	s_add_u32 s38, s38, 0x8000
	s_addc_u32 s39, s39, 0
	s_waitcnt vmcnt(0)
	global_load_dwordx4 v[76:79], v5, s[38:39]
	global_load_dword v60, v6, s[38:39]
	global_load_dword v61, v6, s[38:39] offset:1024
	global_load_dword v62, v6, s[38:39] offset:2048
	global_load_dword v63, v6, s[38:39] offset:3072
	global_load_dword v64, v7, s[38:39]
	global_load_dword v65, v7, s[38:39] offset:1024
	global_load_dword v66, v7, s[38:39] offset:2048
	global_load_dword v67, v7, s[38:39] offset:3072
	global_load_dword v68, v8, s[38:39]
	global_load_dword v69, v8, s[38:39] offset:1024
	global_load_dword v70, v8, s[38:39] offset:2048
	global_load_dword v71, v8, s[38:39] offset:3072
	global_load_dword v72, v9, s[38:39]
	global_load_dword v73, v9, s[38:39] offset:1024
	global_load_dword v74, v9, s[38:39] offset:2048
	global_load_dword v75, v9, s[38:39] offset:3072
	s_add_u32 s38, s38, 0x8000
	s_addc_u32 s39, s39, 0
	global_store_dwordx4 v5, v[12:15], s[40:41]
	s_add_u32 s40, s40, 0x8000
	s_addc_u32 s41, s41, 0
	ds_write_b128 v11, v[12:15]
	v_xor_b32_e32 v11, 0x2000, v11
	s_movk_i32 s10, 20
	s_waitcnt lgkmcnt(0)
	s_barrier
.Lrb1_loop:
	global_load_dwordx4 v[96:99], v5, s[38:39]
	global_load_dword v80, v6, s[38:39]
	global_load_dword v81, v6, s[38:39] offset:1024
	global_load_dword v82, v6, s[38:39] offset:2048
	global_load_dword v83, v6, s[38:39] offset:3072
	global_load_dword v84, v7, s[38:39]
	global_load_dword v85, v7, s[38:39] offset:1024
	global_load_dword v86, v7, s[38:39] offset:2048
	global_load_dword v87, v7, s[38:39] offset:3072
	global_load_dword v88, v8, s[38:39]
	global_load_dword v89, v8, s[38:39] offset:1024
	global_load_dword v90, v8, s[38:39] offset:2048
	global_load_dword v91, v8, s[38:39] offset:3072
	global_load_dword v92, v9, s[38:39]
	global_load_dword v93, v9, s[38:39] offset:1024
	global_load_dword v94, v9, s[38:39] offset:2048
	global_load_dword v95, v9, s[38:39] offset:3072
	s_add_u32 s38, s38, 0x8000
	s_addc_u32 s39, s39, 0
	ds_read2_b32 v[24:25], v10 offset1:4
	ds_read2_b32 v[26:27], v10 offset0:8 offset1:12
	ds_read2_b32 v[28:29], v10 offset0:16 offset1:20
	ds_read2_b32 v[30:31], v10 offset0:24 offset1:28
	ds_read2_b32 v[32:33], v10 offset0:32 offset1:36
	ds_read2_b32 v[34:35], v10 offset0:40 offset1:44
	ds_read2_b32 v[36:37], v10 offset0:48 offset1:52
	ds_read2_b32 v[38:39], v10 offset0:56 offset1:60
	s_waitcnt vmcnt(36)
	s_waitcnt lgkmcnt(7)
	v_mfma_f32_16x16x4_f32 v[16:19], v40, v24, v[56:59]
	v_mfma_f32_16x16x4_f32 v[20:23], v41, v25, 0
	s_waitcnt lgkmcnt(6)
	v_mfma_f32_16x16x4_f32 v[16:19], v42, v26, v[16:19]
	v_mfma_f32_16x16x4_f32 v[20:23], v43, v27, v[20:23]
	s_waitcnt lgkmcnt(5)
	v_mfma_f32_16x16x4_f32 v[16:19], v44, v28, v[16:19]
	v_mfma_f32_16x16x4_f32 v[20:23], v45, v29, v[20:23]
	s_waitcnt lgkmcnt(4)
	v_mfma_f32_16x16x4_f32 v[16:19], v46, v30, v[16:19]
	v_mfma_f32_16x16x4_f32 v[20:23], v47, v31, v[20:23]
	s_waitcnt lgkmcnt(3)
	v_mfma_f32_16x16x4_f32 v[16:19], v48, v32, v[16:19]
	v_mfma_f32_16x16x4_f32 v[20:23], v49, v33, v[20:23]
	s_waitcnt lgkmcnt(2)
	v_mfma_f32_16x16x4_f32 v[16:19], v50, v34, v[16:19]
	v_mfma_f32_16x16x4_f32 v[20:23], v51, v35, v[20:23]
	s_waitcnt lgkmcnt(1)
	v_mfma_f32_16x16x4_f32 v[16:19], v52, v36, v[16:19]
	v_mfma_f32_16x16x4_f32 v[20:23], v53, v37, v[20:23]
	s_waitcnt lgkmcnt(0)
	v_mfma_f32_16x16x4_f32 v[16:19], v54, v38, v[16:19]
	v_mfma_f32_16x16x4_f32 v[20:23], v55, v39, v[20:23]
	v_xor_b32_e32 v10, 0x2000, v10
	s_nop 7
	s_nop 2
	v_add_f32_e32 v12, v16, v20
	v_add_f32_e32 v13, v17, v21
	v_add_f32_e32 v14, v18, v22
	v_add_f32_e32 v15, v19, v23
	s_waitcnt vmcnt(34)
	global_store_dwordx4 v5, v[12:15], s[40:41]
	s_add_u32 s40, s40, 0x8000
	s_addc_u32 s41, s41, 0
	ds_write_b128 v11, v[12:15]
	v_xor_b32_e32 v11, 0x2000, v11
	s_waitcnt lgkmcnt(0)
	s_barrier
	global_load_dwordx4 v[56:59], v5, s[38:39]
	global_load_dword v40, v6, s[38:39]
	global_load_dword v41, v6, s[38:39] offset:1024
	global_load_dword v42, v6, s[38:39] offset:2048
	global_load_dword v43, v6, s[38:39] offset:3072
	global_load_dword v44, v7, s[38:39]
	global_load_dword v45, v7, s[38:39] offset:1024
	global_load_dword v46, v7, s[38:39] offset:2048
	global_load_dword v47, v7, s[38:39] offset:3072
	global_load_dword v48, v8, s[38:39]
	global_load_dword v49, v8, s[38:39] offset:1024
	global_load_dword v50, v8, s[38:39] offset:2048
	global_load_dword v51, v8, s[38:39] offset:3072
	global_load_dword v52, v9, s[38:39]
	global_load_dword v53, v9, s[38:39] offset:1024
	global_load_dword v54, v9, s[38:39] offset:2048
	global_load_dword v55, v9, s[38:39] offset:3072
	s_add_u32 s38, s38, 0x8000
	s_addc_u32 s39, s39, 0
	ds_read2_b32 v[24:25], v10 offset1:4
	ds_read2_b32 v[26:27], v10 offset0:8 offset1:12
	ds_read2_b32 v[28:29], v10 offset0:16 offset1:20
	ds_read2_b32 v[30:31], v10 offset0:24 offset1:28
	ds_read2_b32 v[32:33], v10 offset0:32 offset1:36
	ds_read2_b32 v[34:35], v10 offset0:40 offset1:44
	ds_read2_b32 v[36:37], v10 offset0:48 offset1:52
	ds_read2_b32 v[38:39], v10 offset0:56 offset1:60
	s_waitcnt vmcnt(36)
	s_waitcnt lgkmcnt(7)
	v_mfma_f32_16x16x4_f32 v[16:19], v60, v24, v[76:79]
	v_mfma_f32_16x16x4_f32 v[20:23], v61, v25, 0
	s_waitcnt lgkmcnt(6)
	v_mfma_f32_16x16x4_f32 v[16:19], v62, v26, v[16:19]
	v_mfma_f32_16x16x4_f32 v[20:23], v63, v27, v[20:23]
	s_waitcnt lgkmcnt(5)
	v_mfma_f32_16x16x4_f32 v[16:19], v64, v28, v[16:19]
	v_mfma_f32_16x16x4_f32 v[20:23], v65, v29, v[20:23]
	s_waitcnt lgkmcnt(4)
	v_mfma_f32_16x16x4_f32 v[16:19], v66, v30, v[16:19]
	v_mfma_f32_16x16x4_f32 v[20:23], v67, v31, v[20:23]
	s_waitcnt lgkmcnt(3)
	v_mfma_f32_16x16x4_f32 v[16:19], v68, v32, v[16:19]
	v_mfma_f32_16x16x4_f32 v[20:23], v69, v33, v[20:23]
	s_waitcnt lgkmcnt(2)
	v_mfma_f32_16x16x4_f32 v[16:19], v70, v34, v[16:19]
	v_mfma_f32_16x16x4_f32 v[20:23], v71, v35, v[20:23]
	s_waitcnt lgkmcnt(1)
	v_mfma_f32_16x16x4_f32 v[16:19], v72, v36, v[16:19]
	v_mfma_f32_16x16x4_f32 v[20:23], v73, v37, v[20:23]
	s_waitcnt lgkmcnt(0)
	v_mfma_f32_16x16x4_f32 v[16:19], v74, v38, v[16:19]
	v_mfma_f32_16x16x4_f32 v[20:23], v75, v39, v[20:23]
	v_xor_b32_e32 v10, 0x2000, v10
	s_nop 7
	s_nop 2
	v_add_f32_e32 v12, v16, v20
	v_add_f32_e32 v13, v17, v21
	v_add_f32_e32 v14, v18, v22
	v_add_f32_e32 v15, v19, v23
	s_waitcnt vmcnt(34)
	global_store_dwordx4 v5, v[12:15], s[40:41]
	s_add_u32 s40, s40, 0x8000
	s_addc_u32 s41, s41, 0
	ds_write_b128 v11, v[12:15]
	v_xor_b32_e32 v11, 0x2000, v11
	s_waitcnt lgkmcnt(0)
	s_barrier
	global_load_dwordx4 v[76:79], v5, s[38:39]
	global_load_dword v60, v6, s[38:39]
	global_load_dword v61, v6, s[38:39] offset:1024
	global_load_dword v62, v6, s[38:39] offset:2048
	global_load_dword v63, v6, s[38:39] offset:3072
	global_load_dword v64, v7, s[38:39]
	global_load_dword v65, v7, s[38:39] offset:1024
	global_load_dword v66, v7, s[38:39] offset:2048
	global_load_dword v67, v7, s[38:39] offset:3072
	global_load_dword v68, v8, s[38:39]
	global_load_dword v69, v8, s[38:39] offset:1024
	global_load_dword v70, v8, s[38:39] offset:2048
	global_load_dword v71, v8, s[38:39] offset:3072
	global_load_dword v72, v9, s[38:39]
	global_load_dword v73, v9, s[38:39] offset:1024
	global_load_dword v74, v9, s[38:39] offset:2048
	global_load_dword v75, v9, s[38:39] offset:3072
	s_add_u32 s38, s38, 0x8000
	s_addc_u32 s39, s39, 0
	ds_read2_b32 v[24:25], v10 offset1:4
	ds_read2_b32 v[26:27], v10 offset0:8 offset1:12
	ds_read2_b32 v[28:29], v10 offset0:16 offset1:20
	ds_read2_b32 v[30:31], v10 offset0:24 offset1:28
	ds_read2_b32 v[32:33], v10 offset0:32 offset1:36
	ds_read2_b32 v[34:35], v10 offset0:40 offset1:44
	ds_read2_b32 v[36:37], v10 offset0:48 offset1:52
	ds_read2_b32 v[38:39], v10 offset0:56 offset1:60
	s_waitcnt vmcnt(36)
	s_waitcnt lgkmcnt(7)
	v_mfma_f32_16x16x4_f32 v[16:19], v80, v24, v[96:99]
	v_mfma_f32_16x16x4_f32 v[20:23], v81, v25, 0
	s_waitcnt lgkmcnt(6)
	v_mfma_f32_16x16x4_f32 v[16:19], v82, v26, v[16:19]
	v_mfma_f32_16x16x4_f32 v[20:23], v83, v27, v[20:23]
	s_waitcnt lgkmcnt(5)
	v_mfma_f32_16x16x4_f32 v[16:19], v84, v28, v[16:19]
	v_mfma_f32_16x16x4_f32 v[20:23], v85, v29, v[20:23]
	s_waitcnt lgkmcnt(4)
	v_mfma_f32_16x16x4_f32 v[16:19], v86, v30, v[16:19]
	v_mfma_f32_16x16x4_f32 v[20:23], v87, v31, v[20:23]
	s_waitcnt lgkmcnt(3)
	v_mfma_f32_16x16x4_f32 v[16:19], v88, v32, v[16:19]
	v_mfma_f32_16x16x4_f32 v[20:23], v89, v33, v[20:23]
	s_waitcnt lgkmcnt(2)
	v_mfma_f32_16x16x4_f32 v[16:19], v90, v34, v[16:19]
	v_mfma_f32_16x16x4_f32 v[20:23], v91, v35, v[20:23]
	s_waitcnt lgkmcnt(1)
	v_mfma_f32_16x16x4_f32 v[16:19], v92, v36, v[16:19]
	v_mfma_f32_16x16x4_f32 v[20:23], v93, v37, v[20:23]
	s_waitcnt lgkmcnt(0)
	v_mfma_f32_16x16x4_f32 v[16:19], v94, v38, v[16:19]
	v_mfma_f32_16x16x4_f32 v[20:23], v95, v39, v[20:23]
	v_xor_b32_e32 v10, 0x2000, v10
	s_nop 7
	s_nop 2
	v_add_f32_e32 v12, v16, v20
	v_add_f32_e32 v13, v17, v21
	v_add_f32_e32 v14, v18, v22
	v_add_f32_e32 v15, v19, v23
	s_waitcnt vmcnt(34)
	global_store_dwordx4 v5, v[12:15], s[40:41]
	s_add_u32 s40, s40, 0x8000
	s_addc_u32 s41, s41, 0
	ds_write_b128 v11, v[12:15]
	v_xor_b32_e32 v11, 0x2000, v11
	s_waitcnt lgkmcnt(0)
	s_barrier
	s_sub_u32 s10, s10, 1
	s_cmp_lg_u32 s10, 0
	s_cbranch_scc1 .Lrb1_loop
	global_load_dwordx4 v[96:99], v5, s[38:39]
	global_load_dword v80, v6, s[38:39]
	global_load_dword v81, v6, s[38:39] offset:1024
	global_load_dword v82, v6, s[38:39] offset:2048
	global_load_dword v83, v6, s[38:39] offset:3072
	global_load_dword v84, v7, s[38:39]
	global_load_dword v85, v7, s[38:39] offset:1024
	global_load_dword v86, v7, s[38:39] offset:2048
	global_load_dword v87, v7, s[38:39] offset:3072
	global_load_dword v88, v8, s[38:39]
	global_load_dword v89, v8, s[38:39] offset:1024
	global_load_dword v90, v8, s[38:39] offset:2048
	global_load_dword v91, v8, s[38:39] offset:3072
	global_load_dword v92, v9, s[38:39]
	global_load_dword v93, v9, s[38:39] offset:1024
	global_load_dword v94, v9, s[38:39] offset:2048
	global_load_dword v95, v9, s[38:39] offset:3072
	s_add_u32 s38, s38, 0x8000
	s_addc_u32 s39, s39, 0
	ds_read2_b32 v[24:25], v10 offset1:4
	ds_read2_b32 v[26:27], v10 offset0:8 offset1:12
	ds_read2_b32 v[28:29], v10 offset0:16 offset1:20
	ds_read2_b32 v[30:31], v10 offset0:24 offset1:28
	ds_read2_b32 v[32:33], v10 offset0:32 offset1:36
	ds_read2_b32 v[34:35], v10 offset0:40 offset1:44
	ds_read2_b32 v[36:37], v10 offset0:48 offset1:52
	ds_read2_b32 v[38:39], v10 offset0:56 offset1:60
	s_waitcnt vmcnt(36)
	s_waitcnt lgkmcnt(7)
	v_mfma_f32_16x16x4_f32 v[16:19], v40, v24, v[56:59]
	v_mfma_f32_16x16x4_f32 v[20:23], v41, v25, 0
	s_waitcnt lgkmcnt(6)
	v_mfma_f32_16x16x4_f32 v[16:19], v42, v26, v[16:19]
	v_mfma_f32_16x16x4_f32 v[20:23], v43, v27, v[20:23]
	s_waitcnt lgkmcnt(5)
	v_mfma_f32_16x16x4_f32 v[16:19], v44, v28, v[16:19]
	v_mfma_f32_16x16x4_f32 v[20:23], v45, v29, v[20:23]
	s_waitcnt lgkmcnt(4)
	v_mfma_f32_16x16x4_f32 v[16:19], v46, v30, v[16:19]
	v_mfma_f32_16x16x4_f32 v[20:23], v47, v31, v[20:23]
	s_waitcnt lgkmcnt(3)
	v_mfma_f32_16x16x4_f32 v[16:19], v48, v32, v[16:19]
	v_mfma_f32_16x16x4_f32 v[20:23], v49, v33, v[20:23]
	s_waitcnt lgkmcnt(2)
	v_mfma_f32_16x16x4_f32 v[16:19], v50, v34, v[16:19]
	v_mfma_f32_16x16x4_f32 v[20:23], v51, v35, v[20:23]
	s_waitcnt lgkmcnt(1)
	v_mfma_f32_16x16x4_f32 v[16:19], v52, v36, v[16:19]
	v_mfma_f32_16x16x4_f32 v[20:23], v53, v37, v[20:23]
	s_waitcnt lgkmcnt(0)
	v_mfma_f32_16x16x4_f32 v[16:19], v54, v38, v[16:19]
	v_mfma_f32_16x16x4_f32 v[20:23], v55, v39, v[20:23]
	v_xor_b32_e32 v10, 0x2000, v10
	s_nop 7
	s_nop 2
	v_add_f32_e32 v12, v16, v20
	v_add_f32_e32 v13, v17, v21
	v_add_f32_e32 v14, v18, v22
	v_add_f32_e32 v15, v19, v23
	s_waitcnt vmcnt(34)
	global_store_dwordx4 v5, v[12:15], s[40:41]
	s_add_u32 s40, s40, 0x8000
	s_addc_u32 s41, s41, 0
	ds_write_b128 v11, v[12:15]
	v_xor_b32_e32 v11, 0x2000, v11
	s_waitcnt lgkmcnt(0)
	s_barrier
	ds_read2_b32 v[24:25], v10 offset1:4
	ds_read2_b32 v[26:27], v10 offset0:8 offset1:12
	ds_read2_b32 v[28:29], v10 offset0:16 offset1:20
	ds_read2_b32 v[30:31], v10 offset0:24 offset1:28
	ds_read2_b32 v[32:33], v10 offset0:32 offset1:36
	ds_read2_b32 v[34:35], v10 offset0:40 offset1:44
	ds_read2_b32 v[36:37], v10 offset0:48 offset1:52
	ds_read2_b32 v[38:39], v10 offset0:56 offset1:60
	s_waitcnt vmcnt(19)
	s_waitcnt lgkmcnt(7)
	v_mfma_f32_16x16x4_f32 v[16:19], v60, v24, v[76:79]
	v_mfma_f32_16x16x4_f32 v[20:23], v61, v25, 0
	s_waitcnt lgkmcnt(6)
	v_mfma_f32_16x16x4_f32 v[16:19], v62, v26, v[16:19]
	v_mfma_f32_16x16x4_f32 v[20:23], v63, v27, v[20:23]
	s_waitcnt lgkmcnt(5)
	v_mfma_f32_16x16x4_f32 v[16:19], v64, v28, v[16:19]
	v_mfma_f32_16x16x4_f32 v[20:23], v65, v29, v[20:23]
	s_waitcnt lgkmcnt(4)
	v_mfma_f32_16x16x4_f32 v[16:19], v66, v30, v[16:19]
	v_mfma_f32_16x16x4_f32 v[20:23], v67, v31, v[20:23]
	s_waitcnt lgkmcnt(3)
	v_mfma_f32_16x16x4_f32 v[16:19], v68, v32, v[16:19]
	v_mfma_f32_16x16x4_f32 v[20:23], v69, v33, v[20:23]
	s_waitcnt lgkmcnt(2)
	v_mfma_f32_16x16x4_f32 v[16:19], v70, v34, v[16:19]
	v_mfma_f32_16x16x4_f32 v[20:23], v71, v35, v[20:23]
	s_waitcnt lgkmcnt(1)
	v_mfma_f32_16x16x4_f32 v[16:19], v72, v36, v[16:19]
	v_mfma_f32_16x16x4_f32 v[20:23], v73, v37, v[20:23]
	s_waitcnt lgkmcnt(0)
	v_mfma_f32_16x16x4_f32 v[16:19], v74, v38, v[16:19]
	v_mfma_f32_16x16x4_f32 v[20:23], v75, v39, v[20:23]
	v_xor_b32_e32 v10, 0x2000, v10
	s_nop 7
	s_nop 2
	v_add_f32_e32 v12, v16, v20
	v_add_f32_e32 v13, v17, v21
	v_add_f32_e32 v14, v18, v22
	v_add_f32_e32 v15, v19, v23
	s_waitcnt vmcnt(17)
	global_store_dwordx4 v5, v[12:15], s[40:41]
	s_add_u32 s40, s40, 0x8000
	s_addc_u32 s41, s41, 0
	ds_write_b128 v11, v[12:15]
	v_xor_b32_e32 v11, 0x2000, v11
	s_waitcnt lgkmcnt(0)
	s_barrier
	ds_read2_b32 v[24:25], v10 offset1:4
	ds_read2_b32 v[26:27], v10 offset0:8 offset1:12
	ds_read2_b32 v[28:29], v10 offset0:16 offset1:20
	ds_read2_b32 v[30:31], v10 offset0:24 offset1:28
	ds_read2_b32 v[32:33], v10 offset0:32 offset1:36
	ds_read2_b32 v[34:35], v10 offset0:40 offset1:44
	ds_read2_b32 v[36:37], v10 offset0:48 offset1:52
	ds_read2_b32 v[38:39], v10 offset0:56 offset1:60
	s_waitcnt vmcnt(0)
	s_waitcnt lgkmcnt(7)
	v_mfma_f32_16x16x4_f32 v[16:19], v80, v24, v[96:99]
	v_mfma_f32_16x16x4_f32 v[20:23], v81, v25, 0
	s_waitcnt lgkmcnt(6)
	v_mfma_f32_16x16x4_f32 v[16:19], v82, v26, v[16:19]
	v_mfma_f32_16x16x4_f32 v[20:23], v83, v27, v[20:23]
	s_waitcnt lgkmcnt(5)
	v_mfma_f32_16x16x4_f32 v[16:19], v84, v28, v[16:19]
	v_mfma_f32_16x16x4_f32 v[20:23], v85, v29, v[20:23]
	s_waitcnt lgkmcnt(4)
	v_mfma_f32_16x16x4_f32 v[16:19], v86, v30, v[16:19]
	v_mfma_f32_16x16x4_f32 v[20:23], v87, v31, v[20:23]
	s_waitcnt lgkmcnt(3)
	v_mfma_f32_16x16x4_f32 v[16:19], v88, v32, v[16:19]
	v_mfma_f32_16x16x4_f32 v[20:23], v89, v33, v[20:23]
	s_waitcnt lgkmcnt(2)
	v_mfma_f32_16x16x4_f32 v[16:19], v90, v34, v[16:19]
	v_mfma_f32_16x16x4_f32 v[20:23], v91, v35, v[20:23]
	s_waitcnt lgkmcnt(1)
	v_mfma_f32_16x16x4_f32 v[16:19], v92, v36, v[16:19]
	v_mfma_f32_16x16x4_f32 v[20:23], v93, v37, v[20:23]
	s_waitcnt lgkmcnt(0)
	v_mfma_f32_16x16x4_f32 v[16:19], v94, v38, v[16:19]
	v_mfma_f32_16x16x4_f32 v[20:23], v95, v39, v[20:23]
	v_xor_b32_e32 v10, 0x2000, v10
	s_nop 7
	s_nop 2
	v_add_f32_e32 v12, v16, v20
	v_add_f32_e32 v13, v17, v21
	v_add_f32_e32 v14, v18, v22
	v_add_f32_e32 v15, v19, v23
	s_waitcnt vmcnt(0)
	global_store_dwordx4 v5, v[12:15], s[40:41]
	s_add_u32 s40, s40, 0x8000
	s_addc_u32 s41, s41, 0
	ds_write_b128 v11, v[12:15]
	v_xor_b32_e32 v11, 0x2000, v11
	s_waitcnt lgkmcnt(0)
	s_barrier
	s_branch .Lrb1_done
.Lrb1_helper:
	s_movk_i32 s10, 64
.Lrb1_hloop:
	s_barrier
	s_sub_u32 s10, s10, 1
	s_cmp_lg_u32 s10, 0
	s_cbranch_scc1 .Lrb1_hloop
.Lrb1_done:
.LBB0_737:
	v_readlane_b32 s6, v255, 18
	v_readlane_b32 s7, v255, 19
	s_mov_b32 s4, 0x100000
	s_andn2_b64 vcc, exec, s[6:7]
	v_cndmask_b32_e64 v0, 0, 1, s[6:7]
	v_cmp_ne_u32_e64 s[0:1], 1, v0
	v_readlane_b32 s5, v252, 34
	s_cbranch_vccnz .LBB0_739
	s_mov_b32 s4, 0x10000
	v_readlane_b32 s5, v254, 47
